# adds: K-loop heads of P1/P7/P8 pinned to measured-good code placement (64B line offsets)
# baseline (speedup 1.0000x reference)
; template <class Epi, class Sched, bool ALIGN_EPI = false, bool SP2 = false>
; __device__ __forceinline__ void gemm_phase(PG8_LAS unsigned char* lds, const Gemm g, const Sched& S, const Epi& E) {
;     ...
;         const bool has_next = S.next(ui + 1, nxt);
;         const char* nA = has_next ? (const char*)g.A + (size_t)nxt.pm * tstep : cA; const char* nB = has_next ? (const char*)g.Bt + (size_t)nxt.pn * tstep : cB;
;         for (int t = 0; t < nt; t += 2) {
;             const bool last = (t == nt - 2);
;             const char* a1 = cA + (size_t)(t + 1) * kstep;
;             const char* a2 = last ? nA : cA + (size_t)(t + 2) * kstep; const char* b2 = last ? nB : cB + (size_t)(t + 2) * kstep;
;             const char* a3 = a2 + kstep; const char* b3 = b2 + kstep;
;     ...
; #pragma unroll
;         for (int a = 0; a < 2; ++a)
; #pragma unroll
;             for (int b = 0; b < 2; ++b)
; #pragma unroll
;                 for (int m = 0; m < 4; ++m)
; #pragma unroll
;                     for (int n = 0; n < 2; ++n) acc[a][b][m][n] = (f32x4){0.f, 0.f, 0.f, 0.f};
;         cur = nxt; cA = nA; cB = nB; ++ui;
.LBB0_60:
	s_ashr_i32 s23, s22, 31
	s_lshl_b64 s[40:41], s[22:23], 20
	s_add_u32 s40, s26, s40
	s_addc_u32 s41, s27, s41
	s_and_b64 s[44:45], s[0:1], exec
	s_cselect_b32 s23, s41, s55
	s_cselect_b32 s87, s40, s54
	s_ashr_i32 s21, s20, 31
	s_lshl_b64 s[44:45], s[20:21], 20
	s_add_u32 s44, s34, s44
	s_addc_u32 s45, s35, s45
	s_and_b64 s[70:71], s[0:1], exec
	s_cselect_b32 s21, s45, s69
	s_cselect_b32 s88, s44, s68
	s_add_u32 s54, s54, 0x80080
	s_addc_u32 s55, s55, 0
	s_add_u32 s89, s68, 0x100
	v_mov_b32_e32 v0, 0
	s_addc_u32 s90, s69, 0
	s_mov_b32 s91, -2
	v_mov_b32_e32 v1, v0
	v_mov_b32_e32 v2, v0
	v_mov_b32_e32 v3, v0
	v_mov_b32_e32 v4, v0
	v_mov_b32_e32 v5, v0
	v_mov_b32_e32 v6, v0
	v_mov_b32_e32 v7, v0
	v_mov_b32_e32 v8, v0
	v_mov_b32_e32 v9, v0
	v_mov_b32_e32 v10, v0
	v_mov_b32_e32 v11, v0
	v_mov_b32_e32 v16, v0
	v_mov_b32_e32 v17, v0
	v_mov_b32_e32 v18, v0
	v_mov_b32_e32 v19, v0
	v_mov_b32_e32 v24, v0
	v_mov_b32_e32 v25, v0
	v_mov_b32_e32 v26, v0
	v_mov_b32_e32 v27, v0
	v_mov_b32_e32 v32, v0
	v_mov_b32_e32 v33, v0
	v_mov_b32_e32 v34, v0
	v_mov_b32_e32 v35, v0
	v_mov_b32_e32 v40, v0
	v_mov_b32_e32 v41, v0
	v_mov_b32_e32 v42, v0
	v_mov_b32_e32 v43, v0
	v_mov_b32_e32 v48, v0
	v_mov_b32_e32 v49, v0
	v_mov_b32_e32 v50, v0
	v_mov_b32_e32 v51, v0
	v_mov_b32_e32 v12, v0
	v_mov_b32_e32 v13, v0
	v_mov_b32_e32 v14, v0
	v_mov_b32_e32 v15, v0
	v_mov_b32_e32 v20, v0
	v_mov_b32_e32 v21, v0
	v_mov_b32_e32 v22, v0
	v_mov_b32_e32 v23, v0
	v_mov_b32_e32 v28, v0
	v_mov_b32_e32 v29, v0
	v_mov_b32_e32 v30, v0
	v_mov_b32_e32 v31, v0
	v_mov_b32_e32 v36, v0
	v_mov_b32_e32 v37, v0
	v_mov_b32_e32 v38, v0
	v_mov_b32_e32 v39, v0
	v_mov_b32_e32 v44, v0
	v_mov_b32_e32 v45, v0
	v_mov_b32_e32 v46, v0
	v_mov_b32_e32 v47, v0
	v_mov_b32_e32 v52, v0
	v_mov_b32_e32 v53, v0
	v_mov_b32_e32 v54, v0
	v_mov_b32_e32 v55, v0
	v_mov_b32_e32 v56, v0
	v_mov_b32_e32 v57, v0
	v_mov_b32_e32 v58, v0
	v_mov_b32_e32 v59, v0
	v_mov_b32_e32 v60, v0
	v_mov_b32_e32 v61, v0
	v_mov_b32_e32 v62, v0
	v_mov_b32_e32 v63, v0
	v_mov_b32_e32 v64, v0
	v_mov_b32_e32 v65, v0
	v_mov_b32_e32 v66, v0
	v_mov_b32_e32 v67, v0
	v_mov_b32_e32 v68, v0
	v_mov_b32_e32 v69, v0
	v_mov_b32_e32 v70, v0
	v_mov_b32_e32 v71, v0
	v_mov_b32_e32 v72, v0
	v_mov_b32_e32 v73, v0
	v_mov_b32_e32 v74, v0
	v_mov_b32_e32 v75, v0
	v_mov_b32_e32 v80, v0
	v_mov_b32_e32 v81, v0
	v_mov_b32_e32 v82, v0
	v_mov_b32_e32 v83, v0
	v_mov_b32_e32 v88, v0
	v_mov_b32_e32 v89, v0
	v_mov_b32_e32 v90, v0
	v_mov_b32_e32 v91, v0
	v_mov_b32_e32 v96, v0
	v_mov_b32_e32 v97, v0
	v_mov_b32_e32 v98, v0
	v_mov_b32_e32 v99, v0
	v_mov_b32_e32 v104, v0
	v_mov_b32_e32 v105, v0
	v_mov_b32_e32 v106, v0
	v_mov_b32_e32 v107, v0
	v_mov_b32_e32 v112, v0
	v_mov_b32_e32 v113, v0
	v_mov_b32_e32 v114, v0
	v_mov_b32_e32 v115, v0
	v_mov_b32_e32 v76, v0
	v_mov_b32_e32 v77, v0
	v_mov_b32_e32 v78, v0
	v_mov_b32_e32 v79, v0
	v_mov_b32_e32 v84, v0
	v_mov_b32_e32 v85, v0
	v_mov_b32_e32 v86, v0
	v_mov_b32_e32 v87, v0
	v_mov_b32_e32 v92, v0
	v_mov_b32_e32 v93, v0
	v_mov_b32_e32 v94, v0
	v_mov_b32_e32 v95, v0
	v_mov_b32_e32 v100, v0
	v_mov_b32_e32 v101, v0
	v_mov_b32_e32 v102, v0
	v_mov_b32_e32 v103, v0
	v_mov_b32_e32 v108, v0
	v_mov_b32_e32 v109, v0
	v_mov_b32_e32 v110, v0
	v_mov_b32_e32 v111, v0
	v_mov_b32_e32 v116, v0
	v_mov_b32_e32 v117, v0
	v_mov_b32_e32 v118, v0
	v_mov_b32_e32 v119, v0
	v_mov_b32_e32 v120, v0
	v_mov_b32_e32 v121, v0
	v_mov_b32_e32 v122, v0
	v_mov_b32_e32 v123, v0
	v_mov_b32_e32 v124, v0
	v_mov_b32_e32 v125, v0
	v_mov_b32_e32 v126, v0
	v_mov_b32_e32 v127, v0
	.p2align	6

; template <class Epi, class Sched, bool ALIGN_EPI = false, bool SP2 = false>
; __device__ __forceinline__ void gemm_phase(PG8_LAS unsigned char* lds, const Gemm g, const Sched& S, const Epi& E) {
;     ...
;     for (;;) {
;         const bool has_next = S.next(ui + 1, nxt);
;         const char* nA = has_next ? (const char*)g.A + (size_t)nxt.pm * tstep : cA; const char* nB = has_next ? (const char*)g.Bt + (size_t)nxt.pn * tstep : cB;
;         for (int t = 0; t < nt; t += 2) {
;             const bool last = (t == nt - 2);
;             const char* a1 = cA + (size_t)(t + 1) * kstep;
;             const char* a2 = last ? nA : cA + (size_t)(t + 2) * kstep; const char* b2 = last ? nB : cB + (size_t)(t + 2) * kstep;
;             const char* a3 = a2 + kstep; const char* b3 = b2 + kstep;
;     ...
; #pragma unroll
;         for (int a = 0; a < 2; ++a)
; #pragma unroll
;             for (int b = 0; b < 2; ++b)
; #pragma unroll
;                 for (int m = 0; m < 4; ++m)
; #pragma unroll
;                     for (int n = 0; n < 2; ++n) acc[a][b][m][n] = (f32x4){0.f, 0.f, 0.f, 0.f};
;         cur = nxt; cA = nA; cB = nB; ++ui;
.LBB0_704:
	s_ashr_i32 s21, s20, 31
	s_lshl_b64 s[22:23], s[20:21], 20
	s_add_u32 s22, s3, s22
	s_addc_u32 s23, s40, s23
	s_and_b64 s[24:25], s[0:1], exec
	s_cselect_b32 s21, s23, s31
	s_cselect_b32 s58, s22, s30
	s_ashr_i32 s19, s18, 31
	s_lshl_b64 s[24:25], s[18:19], 20
	s_add_u32 s24, s41, s24
	s_addc_u32 s25, s42, s25
	s_and_b64 s[38:39], s[0:1], exec
	s_cselect_b32 s19, s25, s37
	s_cselect_b32 s59, s24, s36
	s_add_u32 s30, s30, 0x80080
	s_addc_u32 s31, s31, 0
	s_add_u32 s60, s36, 0x100
	v_mov_b32_e32 v4, 0
	s_addc_u32 s61, s37, 0
	s_mov_b32 s62, -2
	v_mov_b32_e32 v5, v4
	v_mov_b32_e32 v6, v4
	v_mov_b32_e32 v7, v4
	v_mov_b32_e32 v12, v4
	v_mov_b32_e32 v13, v4
	v_mov_b32_e32 v14, v4
	v_mov_b32_e32 v15, v4
	v_mov_b32_e32 v20, v4
	v_mov_b32_e32 v21, v4
	v_mov_b32_e32 v22, v4
	v_mov_b32_e32 v23, v4
	v_mov_b32_e32 v28, v4
	v_mov_b32_e32 v29, v4
	v_mov_b32_e32 v30, v4
	v_mov_b32_e32 v31, v4
	v_mov_b32_e32 v36, v4
	v_mov_b32_e32 v37, v4
	v_mov_b32_e32 v38, v4
	v_mov_b32_e32 v39, v4
	v_mov_b32_e32 v44, v4
	v_mov_b32_e32 v45, v4
	v_mov_b32_e32 v46, v4
	v_mov_b32_e32 v47, v4
	v_mov_b32_e32 v52, v4
	v_mov_b32_e32 v53, v4
	v_mov_b32_e32 v54, v4
	v_mov_b32_e32 v55, v4
	v_mov_b32_e32 v60, v4
	v_mov_b32_e32 v61, v4
	v_mov_b32_e32 v62, v4
	v_mov_b32_e32 v63, v4
	v_mov_b32_e32 v0, v4
	v_mov_b32_e32 v1, v4
	v_mov_b32_e32 v2, v4
	v_mov_b32_e32 v3, v4
	v_mov_b32_e32 v8, v4
	v_mov_b32_e32 v9, v4
	v_mov_b32_e32 v10, v4
	v_mov_b32_e32 v11, v4
	v_mov_b32_e32 v16, v4
	v_mov_b32_e32 v17, v4
	v_mov_b32_e32 v18, v4
	v_mov_b32_e32 v19, v4
	v_mov_b32_e32 v24, v4
	v_mov_b32_e32 v25, v4
	v_mov_b32_e32 v26, v4
	v_mov_b32_e32 v27, v4
	v_mov_b32_e32 v32, v4
	v_mov_b32_e32 v33, v4
	v_mov_b32_e32 v34, v4
	v_mov_b32_e32 v35, v4
	v_mov_b32_e32 v40, v4
	v_mov_b32_e32 v41, v4
	v_mov_b32_e32 v42, v4
	v_mov_b32_e32 v43, v4
	v_mov_b32_e32 v48, v4
	v_mov_b32_e32 v49, v4
	v_mov_b32_e32 v50, v4
	v_mov_b32_e32 v51, v4
	v_mov_b32_e32 v56, v4
	v_mov_b32_e32 v57, v4
	v_mov_b32_e32 v58, v4
	v_mov_b32_e32 v59, v4
	v_mov_b32_e32 v68, v4
	v_mov_b32_e32 v69, v4
	v_mov_b32_e32 v70, v4
	v_mov_b32_e32 v71, v4
	v_mov_b32_e32 v76, v4
	v_mov_b32_e32 v77, v4
	v_mov_b32_e32 v78, v4
	v_mov_b32_e32 v79, v4
	v_mov_b32_e32 v88, v4
	v_mov_b32_e32 v89, v4
	v_mov_b32_e32 v90, v4
	v_mov_b32_e32 v91, v4
	v_mov_b32_e32 v92, v4
	v_mov_b32_e32 v93, v4
	v_mov_b32_e32 v94, v4
	v_mov_b32_e32 v95, v4
	v_mov_b32_e32 v104, v4
	v_mov_b32_e32 v105, v4
	v_mov_b32_e32 v106, v4
	v_mov_b32_e32 v107, v4
	v_mov_b32_e32 v108, v4
	v_mov_b32_e32 v109, v4
	v_mov_b32_e32 v110, v4
	v_mov_b32_e32 v111, v4
	v_mov_b32_e32 v120, v4
	v_mov_b32_e32 v121, v4
	v_mov_b32_e32 v122, v4
	v_mov_b32_e32 v123, v4
	v_mov_b32_e32 v124, v4
	v_mov_b32_e32 v125, v4
	v_mov_b32_e32 v126, v4
	v_mov_b32_e32 v127, v4
	v_mov_b32_e32 v64, v4
	v_mov_b32_e32 v65, v4
	v_mov_b32_e32 v66, v4
	v_mov_b32_e32 v67, v4
	v_mov_b32_e32 v72, v4
	v_mov_b32_e32 v73, v4
	v_mov_b32_e32 v74, v4
	v_mov_b32_e32 v75, v4
	v_mov_b32_e32 v80, v4
	v_mov_b32_e32 v81, v4
	v_mov_b32_e32 v82, v4
	v_mov_b32_e32 v83, v4
	v_mov_b32_e32 v84, v4
	v_mov_b32_e32 v85, v4
	v_mov_b32_e32 v86, v4
	v_mov_b32_e32 v87, v4
	v_mov_b32_e32 v96, v4
	v_mov_b32_e32 v97, v4
	v_mov_b32_e32 v98, v4
	v_mov_b32_e32 v99, v4
	v_mov_b32_e32 v100, v4
	v_mov_b32_e32 v101, v4
	v_mov_b32_e32 v102, v4
	v_mov_b32_e32 v103, v4
	v_mov_b32_e32 v112, v4
	v_mov_b32_e32 v113, v4
	v_mov_b32_e32 v114, v4
	v_mov_b32_e32 v115, v4
	v_mov_b32_e32 v116, v4
	v_mov_b32_e32 v117, v4
	v_mov_b32_e32 v118, v4
	v_mov_b32_e32 v119, v4
	.p2align	6
	s_nop 0
	s_nop 0

; template <class Epi, class Sched, bool ALIGN_EPI = false, bool SP2 = false>
; __device__ __forceinline__ void gemm_phase(PG8_LAS unsigned char* lds, const Gemm g, const Sched& S, const Epi& E) {
;     ...
;     for (;;) {
;         const bool has_next = S.next(ui + 1, nxt);
;         const char* nA = has_next ? (const char*)g.A + (size_t)nxt.pm * tstep : cA; const char* nB = has_next ? (const char*)g.Bt + (size_t)nxt.pn * tstep : cB;
;         for (int t = 0; t < nt; t += 2) {
;             const bool last = (t == nt - 2);
;             const char* a1 = cA + (size_t)(t + 1) * kstep;
;             const char* a2 = last ? nA : cA + (size_t)(t + 2) * kstep; const char* b2 = last ? nB : cB + (size_t)(t + 2) * kstep;
;             const char* a3 = a2 + kstep; const char* b3 = b2 + kstep;
;     ...
; #pragma unroll
;         for (int a = 0; a < 2; ++a)
; #pragma unroll
;             for (int b = 0; b < 2; ++b)
; #pragma unroll
;                 for (int m = 0; m < 4; ++m)
; #pragma unroll
;                     for (int n = 0; n < 2; ++n) acc[a][b][m][n] = (f32x4){0.f, 0.f, 0.f, 0.f};
;         cur = nxt; cA = nA; cB = nB; ++ui;
.LBB0_741:
	s_add_u32 s22, s22, 0x160080
	s_addc_u32 s23, s23, 0
	s_add_u32 s55, s24, 0x100
	v_mov_b32_e32 v0, 0
	s_addc_u32 s56, s25, 0
	s_mov_b32 s57, -2
	v_mov_b32_e32 v1, v0
	v_mov_b32_e32 v2, v0
	v_mov_b32_e32 v3, v0
	v_mov_b32_e32 v4, v0
	v_mov_b32_e32 v5, v0
	v_mov_b32_e32 v6, v0
	v_mov_b32_e32 v7, v0
	v_mov_b32_e32 v16, v0
	v_mov_b32_e32 v17, v0
	v_mov_b32_e32 v18, v0
	v_mov_b32_e32 v19, v0
	v_mov_b32_e32 v20, v0
	v_mov_b32_e32 v21, v0
	v_mov_b32_e32 v22, v0
	v_mov_b32_e32 v23, v0
	v_mov_b32_e32 v32, v0
	v_mov_b32_e32 v33, v0
	v_mov_b32_e32 v34, v0
	v_mov_b32_e32 v35, v0
	v_mov_b32_e32 v36, v0
	v_mov_b32_e32 v37, v0
	v_mov_b32_e32 v38, v0
	v_mov_b32_e32 v39, v0
	v_mov_b32_e32 v48, v0
	v_mov_b32_e32 v49, v0
	v_mov_b32_e32 v50, v0
	v_mov_b32_e32 v51, v0
	v_mov_b32_e32 v52, v0
	v_mov_b32_e32 v53, v0
	v_mov_b32_e32 v54, v0
	v_mov_b32_e32 v55, v0
	v_mov_b32_e32 v8, v0
	v_mov_b32_e32 v9, v0
	v_mov_b32_e32 v10, v0
	v_mov_b32_e32 v11, v0
	v_mov_b32_e32 v12, v0
	v_mov_b32_e32 v13, v0
	v_mov_b32_e32 v14, v0
	v_mov_b32_e32 v15, v0
	v_mov_b32_e32 v24, v0
	v_mov_b32_e32 v25, v0
	v_mov_b32_e32 v26, v0
	v_mov_b32_e32 v27, v0
	v_mov_b32_e32 v28, v0
	v_mov_b32_e32 v29, v0
	v_mov_b32_e32 v30, v0
	v_mov_b32_e32 v31, v0
	v_mov_b32_e32 v40, v0
	v_mov_b32_e32 v41, v0
	v_mov_b32_e32 v42, v0
	v_mov_b32_e32 v43, v0
	v_mov_b32_e32 v44, v0
	v_mov_b32_e32 v45, v0
	v_mov_b32_e32 v46, v0
	v_mov_b32_e32 v47, v0
	v_mov_b32_e32 v56, v0
	v_mov_b32_e32 v57, v0
	v_mov_b32_e32 v58, v0
	v_mov_b32_e32 v59, v0
	v_mov_b32_e32 v60, v0
	v_mov_b32_e32 v61, v0
	v_mov_b32_e32 v62, v0
	v_mov_b32_e32 v63, v0
	v_mov_b32_e32 v64, v0
	v_mov_b32_e32 v65, v0
	v_mov_b32_e32 v66, v0
	v_mov_b32_e32 v67, v0
	v_mov_b32_e32 v68, v0
	v_mov_b32_e32 v69, v0
	v_mov_b32_e32 v70, v0
	v_mov_b32_e32 v71, v0
	v_mov_b32_e32 v80, v0
	v_mov_b32_e32 v81, v0
	v_mov_b32_e32 v82, v0
	v_mov_b32_e32 v83, v0
	v_mov_b32_e32 v84, v0
	v_mov_b32_e32 v85, v0
	v_mov_b32_e32 v86, v0
	v_mov_b32_e32 v87, v0
	v_mov_b32_e32 v96, v0
	v_mov_b32_e32 v97, v0
	v_mov_b32_e32 v98, v0
	v_mov_b32_e32 v99, v0
	v_mov_b32_e32 v100, v0
	v_mov_b32_e32 v101, v0
	v_mov_b32_e32 v102, v0
	v_mov_b32_e32 v103, v0
	v_mov_b32_e32 v112, v0
	v_mov_b32_e32 v113, v0
	v_mov_b32_e32 v114, v0
	v_mov_b32_e32 v115, v0
	v_mov_b32_e32 v116, v0
	v_mov_b32_e32 v117, v0
	v_mov_b32_e32 v118, v0
	v_mov_b32_e32 v119, v0
	v_mov_b32_e32 v72, v0
	v_mov_b32_e32 v73, v0
	v_mov_b32_e32 v74, v0
	v_mov_b32_e32 v75, v0
	v_mov_b32_e32 v76, v0
	v_mov_b32_e32 v77, v0
	v_mov_b32_e32 v78, v0
	v_mov_b32_e32 v79, v0
	v_mov_b32_e32 v88, v0
	v_mov_b32_e32 v89, v0
	v_mov_b32_e32 v90, v0
	v_mov_b32_e32 v91, v0
	v_mov_b32_e32 v92, v0
	v_mov_b32_e32 v93, v0
	v_mov_b32_e32 v94, v0
	v_mov_b32_e32 v95, v0
	v_mov_b32_e32 v104, v0
	v_mov_b32_e32 v105, v0
	v_mov_b32_e32 v106, v0
	v_mov_b32_e32 v107, v0
	v_mov_b32_e32 v108, v0
	v_mov_b32_e32 v109, v0
	v_mov_b32_e32 v110, v0
	v_mov_b32_e32 v111, v0
	v_mov_b32_e32 v120, v0
	v_mov_b32_e32 v121, v0
	v_mov_b32_e32 v122, v0
	v_mov_b32_e32 v123, v0
	v_mov_b32_e32 v124, v0
	v_mov_b32_e32 v125, v0
	v_mov_b32_e32 v126, v0
	v_mov_b32_e32 v127, v0
	.p2align	6
	s_nop 0
	s_nop 0
	s_nop 0
	s_nop 0
